# prologue adaLN modulation item: ada_w rows pre-touched so the dependent k-loops hit L2
# baseline (speedup 1.0000x reference)
; DEV void mod_item(const Params& p, int it, char* smem, int tid) {
;     ...
;   for (int half = 0; half < 2; ++half) {
;     __syncthreads();
;     for (int e = tid; e < 33 * 512; e += 512) {
;       int r = e >> 9, kk = e & 511;
;       float v = (r < 32) ? p.c[r * 1024 + half * 512 + kk] : p.c_ctx[half * 512 + kk];
;       sl[e] = v / (1.f + expf(-v));
;     }
;     __syncthreads();
;     const float* wp = p.ada_w + ((long)l * 1024 + half * 512 + ks * 64) * 3072 + c0 + c;
;     for (int kk = 0; kk < 64; ++kk) {
;       float w = wp[(long)kk * 3072];
.LBB0_57:
	s_mul_hi_i32 s30, s97, 0x2aaaaaab
	s_lshr_b32 s31, s30, 31
	s_ashr_i32 s30, s30, 3
	s_add_i32 s30, s30, s31
	s_mul_i32 s31, s30, 48
	s_sub_i32 s31, s97, s31
	s_lshl_b32 s31, s31, 8
	s_mul_i32 s30, s30, 0xc00000
	s_add_u32 s30, s30, s31
	s_add_u32 s30, s50, s30
	s_addc_u32 s31, s51, 0
	v_and_b32_e32 v250, 0xffffffc0, v197
	v_mul_u32_u24_e32 v250, 0x3000, v250
	v_and_b32_e32 v251, 63, v197
	v_lshl_add_u32 v250, v251, 2, v250
	s_movk_i32 s32, 64
.Lmod_pf_a:
	global_load_dword v252, v250, s[30:31]
	s_add_u32 s30, s30, 0x3000
	s_addc_u32 s31, s31, 0
	s_sub_i32 s32, s32, 1
	s_cmp_lg_u32 s32, 0
	s_cbranch_scc1 .Lmod_pf_a
	s_add_u32 s30, s30, 0x540000
	s_addc_u32 s31, s31, 0
	v_and_b32_e32 v56, 0x1ff, v12
	v_max_i32_e32 v2, 0x4000, v12
	v_cmp_gt_i32_e64 s[4:5], s88, v12
	v_lshlrev_b32_e32 v10, 2, v56
	v_sub_u32_e32 v45, v2, v12
	s_barrier
	s_and_saveexec_b64 s[8:9], s[4:5]
	s_cbranch_execz .LBB0_69
	v_add_u32_e32 v5, 0x1ff, v45
	v_lshl_add_u64 v[2:3], s[48:49], 0, v[10:11]
	v_cmp_lt_u32_e32 vcc, s75, v5
	s_mov_b64 s[6:7], -1
	v_mov_b32_e32 v4, v12
	s_and_saveexec_b64 s[10:11], vcc
	s_cbranch_execz .LBB0_66
	v_lshrrev_b32_e32 v6, 9, v5
	v_add_u32_e32 v13, 0x200, v12
	v_add_u32_e32 v7, -1, v6
	v_cmp_lt_u32_e32 vcc, 1, v7
	v_mov_b32_e32 v8, 0
	v_mov_b64_e32 v[4:5], v[12:13]
	s_and_saveexec_b64 s[62:63], vcc
	s_cbranch_execz .LBB0_63
	v_lshrrev_b32_e32 v4, 1, v7
	v_add_u32_e32 v4, 1, v4
	v_and_b32_e32 v8, -2, v4
	v_lshlrev_b32_e32 v9, 2, v12
	s_mov_b32 s42, 0
	s_mov_b64 s[64:65], 0
	v_mov_b64_e32 v[4:5], v[12:13]

; DEV void mod_item(const Params& p, int it, char* smem, int tid) {
;     ...
;     for (int kk = 0; kk < 64; ++kk) {
;       float w = wp[(long)kk * 3072];
;       const float* sp = sl + ks * 64 + kk;
; #pragma unroll
;       for (int r = 0; r < 33; ++r) acc[r] = fmaf(sp[r * 512], w, acc[r]);
.LBB0_70:
	v_add_co_u32_e32 v82, vcc, s71, v42
	global_load_dword v44, v[42:43], off
	v_add_u32_e32 v13, s7, v3
	v_addc_co_u32_e32 v83, vcc, 0, v43, vcc
	ds_read2st64_b64 v[58:61], v13 offset1:4
	ds_read2st64_b64 v[62:65], v13 offset0:8 offset1:12
	ds_read2st64_b64 v[66:69], v13 offset0:16 offset1:20
	ds_read2st64_b64 v[70:73], v13 offset0:24 offset1:28
	ds_read2st64_b64 v[74:77], v13 offset0:32 offset1:36
	ds_read2st64_b64 v[78:81], v13 offset0:40 offset1:44
	global_load_dword v122, v[82:83], off
	global_load_dword v252, v250, s[30:31]
	s_add_u32 s30, s30, 0x3000
	s_addc_u32 s31, s31, 0
	global_load_dword v252, v250, s[30:31]
	s_add_u32 s30, s30, 0x3000
	s_addc_u32 s31, s31, 0
	ds_read2st64_b64 v[82:85], v13 offset0:48 offset1:52
	ds_read2st64_b64 v[86:89], v13 offset0:56 offset1:60
	ds_read2st64_b64 v[90:93], v13 offset0:64 offset1:68
	ds_read2st64_b64 v[94:97], v13 offset0:72 offset1:76
	ds_read2st64_b64 v[98:101], v13 offset0:80 offset1:84
	ds_read2st64_b64 v[102:105], v13 offset0:88 offset1:92
	ds_read2st64_b64 v[106:109], v13 offset0:96 offset1:100
	ds_read2st64_b64 v[110:113], v13 offset0:104 offset1:108
	ds_read2st64_b64 v[114:117], v13 offset0:112 offset1:116
	ds_read2st64_b64 v[118:121], v13 offset0:120 offset1:124
	v_add_u32_e32 v13, 0x10000, v13
	ds_read_b64 v[124:125], v13
	s_waitcnt lgkmcnt(14)
	v_mov_b32_e32 v126, v62
	v_mov_b32_e32 v127, v60
	v_mov_b32_e32 v128, v66
	v_mov_b32_e32 v129, v64
	s_waitcnt lgkmcnt(13)
	v_mov_b32_e32 v130, v70
	v_mov_b32_e32 v131, v68
	s_waitcnt lgkmcnt(12)
	v_mov_b32_e32 v132, v74
	v_mov_b32_e32 v133, v72
	s_waitcnt lgkmcnt(11)
	v_mov_b32_e32 v134, v78
	v_mov_b32_e32 v135, v76
	s_waitcnt lgkmcnt(10)
	v_mov_b32_e32 v136, v82
	v_mov_b32_e32 v137, v80
	s_waitcnt lgkmcnt(9)
	v_mov_b32_e32 v138, v86
	v_mov_b32_e32 v139, v84
	s_waitcnt lgkmcnt(8)
	v_mov_b32_e32 v140, v90
	v_mov_b32_e32 v141, v88
	s_waitcnt lgkmcnt(7)
	v_mov_b32_e32 v142, v94
	v_mov_b32_e32 v143, v92
	s_waitcnt lgkmcnt(6)
	v_mov_b32_e32 v144, v98
	v_mov_b32_e32 v145, v96
	s_waitcnt lgkmcnt(5)
	v_mov_b32_e32 v146, v102
	v_mov_b32_e32 v147, v100
	s_waitcnt lgkmcnt(4)
	v_mov_b32_e32 v148, v106
	v_mov_b32_e32 v149, v104
	s_waitcnt lgkmcnt(3)
	v_mov_b32_e32 v150, v110
	v_mov_b32_e32 v151, v108
	s_waitcnt lgkmcnt(2)
	v_mov_b32_e32 v152, v114
	v_mov_b32_e32 v153, v112
	s_waitcnt lgkmcnt(1)
	v_mov_b32_e32 v154, v118
	v_mov_b32_e32 v155, v116
	v_mov_b32_e32 v157, v120
	s_waitcnt lgkmcnt(0)
	v_mov_b32_e32 v156, v124
	s_add_i32 s7, s7, 8
	v_mov_b32_e32 v60, v63
	v_mov_b32_e32 v64, v67
	v_mov_b32_e32 v68, v71
	v_mov_b32_e32 v72, v75
	v_mov_b32_e32 v76, v79
	v_mov_b32_e32 v80, v83
	v_mov_b32_e32 v84, v87
	v_mov_b32_e32 v88, v91
	v_mov_b32_e32 v92, v95
	v_mov_b32_e32 v96, v99
	v_mov_b32_e32 v100, v103
	v_mov_b32_e32 v104, v107
	v_mov_b32_e32 v108, v111
	v_mov_b32_e32 v112, v115
	v_mov_b32_e32 v116, v119
	v_mov_b32_e32 v120, v125
	v_lshl_add_u64 v[42:43], v[42:43], 0, s[60:61]
	s_cmpk_eq_i32 s7, 0x100
	s_waitcnt vmcnt(3)
	v_fmac_f32_e32 v57, v58, v44
	v_pk_fma_f32 v[38:39], v[126:127], v[44:45], v[38:39] op_sel_hi:[1,0,1]
	v_pk_fma_f32 v[36:37], v[128:129], v[44:45], v[36:37] op_sel_hi:[1,0,1]
	v_pk_fma_f32 v[34:35], v[130:131], v[44:45], v[34:35] op_sel_hi:[1,0,1]
	v_pk_fma_f32 v[32:33], v[132:133], v[44:45], v[32:33] op_sel_hi:[1,0,1]
	v_pk_fma_f32 v[30:31], v[134:135], v[44:45], v[30:31] op_sel_hi:[1,0,1]
	v_pk_fma_f32 v[28:29], v[136:137], v[44:45], v[28:29] op_sel_hi:[1,0,1]
	v_pk_fma_f32 v[26:27], v[138:139], v[44:45], v[26:27] op_sel_hi:[1,0,1]
	v_pk_fma_f32 v[24:25], v[140:141], v[44:45], v[24:25] op_sel_hi:[1,0,1]
	v_pk_fma_f32 v[22:23], v[142:143], v[44:45], v[22:23] op_sel_hi:[1,0,1]
	v_pk_fma_f32 v[20:21], v[144:145], v[44:45], v[20:21] op_sel_hi:[1,0,1]
	v_pk_fma_f32 v[18:19], v[146:147], v[44:45], v[18:19] op_sel_hi:[1,0,1]
	v_pk_fma_f32 v[16:17], v[148:149], v[44:45], v[16:17] op_sel_hi:[1,0,1]
	v_pk_fma_f32 v[14:15], v[150:151], v[44:45], v[14:15] op_sel_hi:[1,0,1]
	v_pk_fma_f32 v[8:9], v[152:153], v[44:45], v[8:9] op_sel_hi:[1,0,1]
	v_pk_fma_f32 v[6:7], v[154:155], v[44:45], v[6:7] op_sel_hi:[1,0,1]
	v_pk_fma_f32 v[4:5], v[156:157], v[44:45], v[4:5] op_sel_hi:[1,0,1]
	s_waitcnt vmcnt(2)
	v_fmac_f32_e32 v57, v59, v122
	v_pk_fma_f32 v[38:39], v[60:61], v[122:123], v[38:39] op_sel_hi:[1,0,1]
	v_pk_fma_f32 v[36:37], v[64:65], v[122:123], v[36:37] op_sel_hi:[1,0,1]
	v_pk_fma_f32 v[34:35], v[68:69], v[122:123], v[34:35] op_sel_hi:[1,0,1]
	v_pk_fma_f32 v[32:33], v[72:73], v[122:123], v[32:33] op_sel_hi:[1,0,1]
	v_pk_fma_f32 v[30:31], v[76:77], v[122:123], v[30:31] op_sel_hi:[1,0,1]
	v_pk_fma_f32 v[28:29], v[80:81], v[122:123], v[28:29] op_sel_hi:[1,0,1]
	v_pk_fma_f32 v[26:27], v[84:85], v[122:123], v[26:27] op_sel_hi:[1,0,1]
	v_pk_fma_f32 v[24:25], v[88:89], v[122:123], v[24:25] op_sel_hi:[1,0,1]
	v_pk_fma_f32 v[22:23], v[92:93], v[122:123], v[22:23] op_sel_hi:[1,0,1]
	v_pk_fma_f32 v[20:21], v[96:97], v[122:123], v[20:21] op_sel_hi:[1,0,1]
	v_pk_fma_f32 v[18:19], v[100:101], v[122:123], v[18:19] op_sel_hi:[1,0,1]
	v_pk_fma_f32 v[16:17], v[104:105], v[122:123], v[16:17] op_sel_hi:[1,0,1]
	v_pk_fma_f32 v[14:15], v[108:109], v[122:123], v[14:15] op_sel_hi:[1,0,1]
	v_pk_fma_f32 v[8:9], v[112:113], v[122:123], v[8:9] op_sel_hi:[1,0,1]
	v_pk_fma_f32 v[6:7], v[116:117], v[122:123], v[6:7] op_sel_hi:[1,0,1]
	v_pk_fma_f32 v[4:5], v[120:121], v[122:123], v[4:5] op_sel_hi:[1,0,1]
	s_cbranch_scc0 .LBB0_70
	s_barrier
	s_and_saveexec_b64 s[10:11], s[4:5]
	s_cbranch_execz .LBB0_83
	v_add_u32_e32 v13, 0x1ff, v45
	v_lshl_add_u64 v[42:43], s[48:49], 0, v[10:11]
	v_cmp_lt_u32_e32 vcc, s75, v13
	s_mov_b64 s[4:5], -1
	v_mov_b32_e32 v10, v12
	s_and_saveexec_b64 s[62:63], vcc
	s_cbranch_execz .LBB0_80
	v_lshrrev_b32_e32 v10, 9, v13
	v_add_u32_e32 v13, 0x200, v12
	v_add_u32_e32 v58, -1, v10
	v_cmp_lt_u32_e32 vcc, 1, v58
	v_mov_b32_e32 v59, 0
	v_mov_b64_e32 v[44:45], v[12:13]
	s_and_saveexec_b64 s[64:65], vcc
	s_cbranch_execz .LBB0_77
	v_lshrrev_b32_e32 v44, 1, v58
	v_add_u32_e32 v44, 1, v44
	v_and_b32_e32 v59, -2, v44
	v_lshlrev_b32_e32 v60, 2, v12
	s_mov_b32 s7, 0
	s_mov_b64 s[66:67], 0
	v_mov_b64_e32 v[44:45], v[12:13]
